# p_mods: 32 ada_w rows in flight per wave per iteration (was 8), saddr loads, plain fmac instead of pk_fma+shuffles
# speedup vs baseline: 1.0114x; 1.0011x over previous
; DI void p_mods(const float* c, const float* cctx, const float* ada_w, const float* ada_b, float* mods, LAS float* sl, int bx, int G) {
;     ...
;     for (int it = bx; it < 4 * 96; it += G) {
;         const int l = it / 96, jb = it % 96, j = jb * 64 + lane, k0 = wave * 128;
;         const float* wp = ada_w + ((size_t)l * DM + k0) * NMOD + j;
;         float a0 = 0.f, a1 = 0.f, a2 = 0.f;
; #pragma unroll 8
;         for (int k = 0; k < 128; ++k) { const float w = wp[(size_t)k * NMOD]; a0 += sl[k0 + k] * w; a1 += sl[DM + k0 + k] * w; a2 += sl[2 * DM + k0 + k] * w; }
.LBB0_14:
	s_mul_hi_i32 s0, s23, 0x2aaaaaab
	s_lshr_b32 s1, s0, 31
	s_ashr_i32 s0, s0, 4
	s_add_i32 s8, s0, s1
	s_mul_i32 s0, s8, 0x60
	s_sub_i32 s0, s23, s0
	s_ashr_i32 s9, s8, 31
	v_lshl_or_b32 v4, s0, 6, v1
	s_lshl_b64 s[0:1], s[8:9], 10
	s_add_u32 s0, s0, s12
	s_addc_u32 s1, s1, s13
	s_mulk_i32 s1, 0x6000
	s_mul_hi_u32 s9, s0, 0x6000
	s_add_i32 s9, s9, s1
	s_mulk_i32 s0, 0x6000
	s_add_u32 s0, s48, s0
	s_addc_u32 s1, s49, s9
	v_ashrrev_i32_e32 v5, 31, v4
	v_mov_b32_e32 v12, 0
	v_lshlrev_b32_e32 v6, 2, v4
	s_mov_b64 s[10:11], s[0:1]
	s_mov_b32 s9, s15
	v_mov_b32_e32 v8, 0
	v_mov_b32_e32 v9, v12
	s_mov_b32 s17, 4
my_mods_loop:
	v_mov_b32_e32 v13, s9
	global_load_dword v38, v6, s[10:11]
	s_add_u32 s10, s10, 0x6000
	s_addc_u32 s11, s11, 0
	global_load_dword v39, v6, s[10:11]
	s_add_u32 s10, s10, 0x6000
	s_addc_u32 s11, s11, 0
	global_load_dword v40, v6, s[10:11]
	s_add_u32 s10, s10, 0x6000
	s_addc_u32 s11, s11, 0
	global_load_dword v41, v6, s[10:11]
	s_add_u32 s10, s10, 0x6000
	s_addc_u32 s11, s11, 0
	global_load_dword v42, v6, s[10:11]
	s_add_u32 s10, s10, 0x6000
	s_addc_u32 s11, s11, 0
	global_load_dword v43, v6, s[10:11]
	s_add_u32 s10, s10, 0x6000
	s_addc_u32 s11, s11, 0
	global_load_dword v44, v6, s[10:11]
	s_add_u32 s10, s10, 0x6000
	s_addc_u32 s11, s11, 0
	global_load_dword v45, v6, s[10:11]
	s_add_u32 s10, s10, 0x6000
	s_addc_u32 s11, s11, 0
	global_load_dword v46, v6, s[10:11]
	s_add_u32 s10, s10, 0x6000
	s_addc_u32 s11, s11, 0
	global_load_dword v47, v6, s[10:11]
	s_add_u32 s10, s10, 0x6000
	s_addc_u32 s11, s11, 0
	global_load_dword v48, v6, s[10:11]
	s_add_u32 s10, s10, 0x6000
	s_addc_u32 s11, s11, 0
	global_load_dword v49, v6, s[10:11]
	s_add_u32 s10, s10, 0x6000
	s_addc_u32 s11, s11, 0
	global_load_dword v50, v6, s[10:11]
	s_add_u32 s10, s10, 0x6000
	s_addc_u32 s11, s11, 0
	global_load_dword v51, v6, s[10:11]
	s_add_u32 s10, s10, 0x6000
	s_addc_u32 s11, s11, 0
	global_load_dword v52, v6, s[10:11]
	s_add_u32 s10, s10, 0x6000
	s_addc_u32 s11, s11, 0
	global_load_dword v53, v6, s[10:11]
	s_add_u32 s10, s10, 0x6000
	s_addc_u32 s11, s11, 0
	global_load_dword v54, v6, s[10:11]
	s_add_u32 s10, s10, 0x6000
	s_addc_u32 s11, s11, 0
	global_load_dword v55, v6, s[10:11]
	s_add_u32 s10, s10, 0x6000
	s_addc_u32 s11, s11, 0
	global_load_dword v56, v6, s[10:11]
	s_add_u32 s10, s10, 0x6000
	s_addc_u32 s11, s11, 0
	global_load_dword v57, v6, s[10:11]
	s_add_u32 s10, s10, 0x6000
	s_addc_u32 s11, s11, 0
	global_load_dword v58, v6, s[10:11]
	s_add_u32 s10, s10, 0x6000
	s_addc_u32 s11, s11, 0
	global_load_dword v59, v6, s[10:11]
	s_add_u32 s10, s10, 0x6000
	s_addc_u32 s11, s11, 0
	global_load_dword v60, v6, s[10:11]
	s_add_u32 s10, s10, 0x6000
	s_addc_u32 s11, s11, 0
	global_load_dword v61, v6, s[10:11]
	s_add_u32 s10, s10, 0x6000
	s_addc_u32 s11, s11, 0
	global_load_dword v62, v6, s[10:11]
	s_add_u32 s10, s10, 0x6000
	s_addc_u32 s11, s11, 0
	global_load_dword v63, v6, s[10:11]
	s_add_u32 s10, s10, 0x6000
	s_addc_u32 s11, s11, 0
	global_load_dword v64, v6, s[10:11]
	s_add_u32 s10, s10, 0x6000
	s_addc_u32 s11, s11, 0
	global_load_dword v65, v6, s[10:11]
	s_add_u32 s10, s10, 0x6000
	s_addc_u32 s11, s11, 0
	global_load_dword v66, v6, s[10:11]
	s_add_u32 s10, s10, 0x6000
	s_addc_u32 s11, s11, 0
	global_load_dword v67, v6, s[10:11]
	s_add_u32 s10, s10, 0x6000
	s_addc_u32 s11, s11, 0
	global_load_dword v68, v6, s[10:11]
	s_add_u32 s10, s10, 0x6000
	s_addc_u32 s11, s11, 0
	global_load_dword v69, v6, s[10:11]
	s_add_u32 s10, s10, 0x6000
	s_addc_u32 s11, s11, 0
	ds_read_b128 v[70:73], v13 offset:0
	ds_read_b128 v[74:77], v13 offset:16
	ds_read_b128 v[78:81], v13 offset:32
	ds_read_b128 v[82:85], v13 offset:48
	ds_read_b128 v[86:89], v13 offset:64
	ds_read_b128 v[90:93], v13 offset:80
	ds_read_b128 v[94:97], v13 offset:96
	ds_read_b128 v[98:101], v13 offset:112
	ds_read_b128 v[102:105], v13 offset:4096
	ds_read_b128 v[106:109], v13 offset:4112
	ds_read_b128 v[110:113], v13 offset:4128
	ds_read_b128 v[114:117], v13 offset:4144
	ds_read_b128 v[118:121], v13 offset:4160
	ds_read_b128 v[122:125], v13 offset:4176
	ds_read_b128 v[126:129], v13 offset:4192
	ds_read_b128 v[130:133], v13 offset:4208
	ds_read_b128 v[134:137], v13 offset:8192
	ds_read_b128 v[138:141], v13 offset:8208
	ds_read_b128 v[142:145], v13 offset:8224
	ds_read_b128 v[146:149], v13 offset:8240
	ds_read_b128 v[150:153], v13 offset:8256
	ds_read_b128 v[154:157], v13 offset:8272
	ds_read_b128 v[158:161], v13 offset:8288
	ds_read_b128 v[162:165], v13 offset:8304
	s_add_i32 s9, s9, 0x80
	s_add_i32 s17, s17, -1
	s_waitcnt lgkmcnt(0)
	s_waitcnt vmcnt(31)
	v_fmac_f32_e32 v12, v38, v70
	v_fmac_f32_e32 v9, v38, v102
	v_fmac_f32_e32 v8, v38, v134
	s_waitcnt vmcnt(30)
; DI void p_mods(const float* c, const float* cctx, const float* ada_w, const float* ada_b, float* mods, LAS float* sl, int bx, int G) {
;     ...
;         for (int k = 0; k < 128; ++k) { const float w = wp[(size_t)k * NMOD]; a0 += sl[k0 + k] * w; a1 += sl[DM + k0 + k] * w; a2 += sl[2 * DM + k0 + k] * w; }
;         part[(wave * 3 + 0) * 64 + lane] = a0; part[(wave * 3 + 1) * 64 + lane] = a1; part[(wave * 3 + 2) * 64 + lane] = a2;
;         __syncthreads();
;         if (tid < 192) { const int wh = tid >> 6; float s = ada_b[l * NMOD + j];
; #pragma unroll
;             for (int q = 0; q < 8; ++q) s += part[(q * 3 + wh) * 64 + lane];
;             mods[((size_t)l * 3 + wh) * NMOD + j] = s; }
;         __syncthreads();
	v_fmac_f32_e32 v12, v39, v71
	v_fmac_f32_e32 v9, v39, v103
	v_fmac_f32_e32 v8, v39, v135
	s_waitcnt vmcnt(29)
	v_fmac_f32_e32 v12, v40, v72
	v_fmac_f32_e32 v9, v40, v104
	v_fmac_f32_e32 v8, v40, v136
	s_waitcnt vmcnt(28)
	v_fmac_f32_e32 v12, v41, v73
	v_fmac_f32_e32 v9, v41, v105
	v_fmac_f32_e32 v8, v41, v137
	s_waitcnt vmcnt(27)
	v_fmac_f32_e32 v12, v42, v74
	v_fmac_f32_e32 v9, v42, v106
	v_fmac_f32_e32 v8, v42, v138
	s_waitcnt vmcnt(26)
	v_fmac_f32_e32 v12, v43, v75
	v_fmac_f32_e32 v9, v43, v107
	v_fmac_f32_e32 v8, v43, v139
	s_waitcnt vmcnt(25)
	v_fmac_f32_e32 v12, v44, v76
	v_fmac_f32_e32 v9, v44, v108
	v_fmac_f32_e32 v8, v44, v140
	s_waitcnt vmcnt(24)
	v_fmac_f32_e32 v12, v45, v77
	v_fmac_f32_e32 v9, v45, v109
	v_fmac_f32_e32 v8, v45, v141
	s_waitcnt vmcnt(23)
	v_fmac_f32_e32 v12, v46, v78
	v_fmac_f32_e32 v9, v46, v110
	v_fmac_f32_e32 v8, v46, v142
	s_waitcnt vmcnt(22)
	v_fmac_f32_e32 v12, v47, v79
	v_fmac_f32_e32 v9, v47, v111
	v_fmac_f32_e32 v8, v47, v143
	s_waitcnt vmcnt(21)
	v_fmac_f32_e32 v12, v48, v80
	v_fmac_f32_e32 v9, v48, v112
	v_fmac_f32_e32 v8, v48, v144
	s_waitcnt vmcnt(20)
	v_fmac_f32_e32 v12, v49, v81
	v_fmac_f32_e32 v9, v49, v113
	v_fmac_f32_e32 v8, v49, v145
	s_waitcnt vmcnt(19)
	v_fmac_f32_e32 v12, v50, v82
	v_fmac_f32_e32 v9, v50, v114
	v_fmac_f32_e32 v8, v50, v146
	s_waitcnt vmcnt(18)
	v_fmac_f32_e32 v12, v51, v83
	v_fmac_f32_e32 v9, v51, v115
	v_fmac_f32_e32 v8, v51, v147
	s_waitcnt vmcnt(17)
	v_fmac_f32_e32 v12, v52, v84
	v_fmac_f32_e32 v9, v52, v116
	v_fmac_f32_e32 v8, v52, v148
	s_waitcnt vmcnt(16)
	v_fmac_f32_e32 v12, v53, v85
	v_fmac_f32_e32 v9, v53, v117
	v_fmac_f32_e32 v8, v53, v149
	s_waitcnt vmcnt(15)
	v_fmac_f32_e32 v12, v54, v86
	v_fmac_f32_e32 v9, v54, v118
	v_fmac_f32_e32 v8, v54, v150
	s_waitcnt vmcnt(14)
	v_fmac_f32_e32 v12, v55, v87
	v_fmac_f32_e32 v9, v55, v119
	v_fmac_f32_e32 v8, v55, v151
	s_waitcnt vmcnt(13)
	v_fmac_f32_e32 v12, v56, v88
	v_fmac_f32_e32 v9, v56, v120
	v_fmac_f32_e32 v8, v56, v152
	s_waitcnt vmcnt(12)
	v_fmac_f32_e32 v12, v57, v89
	v_fmac_f32_e32 v9, v57, v121
	v_fmac_f32_e32 v8, v57, v153
	s_waitcnt vmcnt(11)
	v_fmac_f32_e32 v12, v58, v90
	v_fmac_f32_e32 v9, v58, v122
	v_fmac_f32_e32 v8, v58, v154
	s_waitcnt vmcnt(10)
	v_fmac_f32_e32 v12, v59, v91
	v_fmac_f32_e32 v9, v59, v123
	v_fmac_f32_e32 v8, v59, v155
	s_waitcnt vmcnt(9)
	v_fmac_f32_e32 v12, v60, v92
	v_fmac_f32_e32 v9, v60, v124
	v_fmac_f32_e32 v8, v60, v156
	s_waitcnt vmcnt(8)
	v_fmac_f32_e32 v12, v61, v93
	v_fmac_f32_e32 v9, v61, v125
	v_fmac_f32_e32 v8, v61, v157
	s_waitcnt vmcnt(7)
	v_fmac_f32_e32 v12, v62, v94
	v_fmac_f32_e32 v9, v62, v126
	v_fmac_f32_e32 v8, v62, v158
	s_waitcnt vmcnt(6)
	v_fmac_f32_e32 v12, v63, v95
	v_fmac_f32_e32 v9, v63, v127
	v_fmac_f32_e32 v8, v63, v159
	s_waitcnt vmcnt(5)
	v_fmac_f32_e32 v12, v64, v96
	v_fmac_f32_e32 v9, v64, v128
	v_fmac_f32_e32 v8, v64, v160
	s_waitcnt vmcnt(4)
	v_fmac_f32_e32 v12, v65, v97
	v_fmac_f32_e32 v9, v65, v129
	v_fmac_f32_e32 v8, v65, v161
	s_waitcnt vmcnt(3)
	v_fmac_f32_e32 v12, v66, v98
	v_fmac_f32_e32 v9, v66, v130
	v_fmac_f32_e32 v8, v66, v162
	s_waitcnt vmcnt(2)
	v_fmac_f32_e32 v12, v67, v99
	v_fmac_f32_e32 v9, v67, v131
	v_fmac_f32_e32 v8, v67, v163
	s_waitcnt vmcnt(1)
	v_fmac_f32_e32 v12, v68, v100
	v_fmac_f32_e32 v9, v68, v132
	v_fmac_f32_e32 v8, v68, v164
	s_waitcnt vmcnt(0)
	v_fmac_f32_e32 v12, v69, v101
	v_fmac_f32_e32 v9, v69, v133
	v_fmac_f32_e32 v8, v69, v165
	s_cmp_lg_u32 s17, 0
	s_cbranch_scc1 my_mods_loop
	ds_write2st64_b32 v10, v12, v9 offset0:48 offset1:49
	ds_write_b32 v10, v8 offset:12800
	s_waitcnt lgkmcnt(0)
	s_barrier
	s_and_saveexec_b64 s[0:1], vcc
	s_cbranch_execz .LBB0_13
	s_mul_i32 s9, s8, 0x1800
	v_add_u32_e32 v6, s9, v4
	v_ashrrev_i32_e32 v7, 31, v6
	v_lshl_add_u64 v[6:7], v[6:7], 2, s[50:51]
	global_load_dword v20, v[6:7], off
	ds_read2st64_b32 v[6:7], v11 offset0:48 offset1:51
	ds_read2st64_b32 v[8:9], v11 offset0:54 offset1:57
	ds_read2st64_b32 v[12:13], v11 offset0:60 offset1:63
	ds_read2st64_b32 v[14:15], v11 offset0:66 offset1:69
	v_mad_i64_i32 v[16:17], s[8:9], s8, 3, v[2:3]
	v_mov_b64_e32 v[18:19], s[36:37]
	v_mad_u64_u32 v[18:19], s[8:9], v16, s16, v[18:19]
	v_mad_i32_i24 v19, v17, s16, v19
	v_lshl_add_u64 v[4:5], v[4:5], 2, v[18:19]
	s_waitcnt vmcnt(0) lgkmcnt(3)
	v_add_f32_e32 v6, v20, v6
	v_add_f32_e32 v6, v6, v7
	s_waitcnt lgkmcnt(2)
	v_add_f32_e32 v6, v6, v8
	v_add_f32_e32 v6, v6, v9
	s_waitcnt lgkmcnt(1)
	v_add_f32_e32 v6, v6, v12
	v_add_f32_e32 v6, v6, v13
	s_waitcnt lgkmcnt(0)
	v_add_f32_e32 v6, v6, v14
	v_add_f32_e32 v6, v6, v15
	global_store_dword v[4:5], v6, off
	s_branch .LBB0_13
